# mLSTM combine (E2) row loop: each wave loads its next row into a second register set while it works on the current row
# speedup vs baseline: 1.0050x; 1.0050x over previous
.LBB0_1350:
	s_or_b64 exec, exec, s[2:3]
	v_mov_b32_e32 v10, v246
	s_waitcnt lgkmcnt(0)
	s_barrier
	v_readlane_b32 s2, v252, 0
	v_ashrrev_i32_e32 v0, 6, v10
	v_readlane_b32 s14, v255, 3
	v_add_u32_e32 v8, s2, v0
	s_nop 0
	v_cmp_gt_i32_e32 vcc, s14, v8
	s_and_saveexec_b64 s[2:3], vcc
	v_readlane_b32 s8, v254, 42
	v_readlane_b32 s9, v254, 43
	v_readlane_b32 s10, v254, 25
	v_readlane_b32 s12, v254, 38
	v_readlane_b32 s11, v254, 26
	s_mov_b32 s9, 0x800000
	v_readlane_b32 s13, v254, 39
	s_cbranch_execz .LBB0_1353
	s_load_dwordx2 s[6:7], s[84:85], 0x58
	v_readlane_b32 s16, v255, 21
	v_lshlrev_b32_e32 v0, 5, v10
	v_readlane_b32 s17, v255, 22
	v_and_b32_e32 v4, 0x7e0, v0
	s_waitcnt lgkmcnt(0)
	s_add_u32 s6, s6, s16
	s_addc_u32 s7, s7, s17
	global_load_dwordx4 v[0:3], v4, s[6:7] offset:16
	s_nop 0
	global_load_dwordx4 v[4:7], v4, s[6:7]
	v_ashrrev_i32_e32 v9, 31, v8
	v_lshlrev_b64 v[12:13], 10, v[8:9]
	v_lshlrev_b32_e32 v9, 4, v10
	v_and_b32_e32 v112, 0x3f0, v9
	v_or_b32_e32 v12, v12, v112
	v_lshl_add_u64 v[10:11], s[18:19], 0, v[12:13]
	v_mad_i64_i32 v[12:13], s[6:7], v8, s33, v[112:113]
	v_lshl_add_u64 v[12:13], s[88:89], 0, v[12:13]
	s_mov_b64 s[6:7], 0x7600800
	v_lshl_add_u64 v[12:13], v[12:13], 0, s[6:7]
	s_mov_b64 s[6:7], 0
	v_mov_b64_e32 v[52:53], v[12:13]
	global_load_dwordx4 v[40:43], v[52:53], off
	global_load_dwordx4 v[44:47], v[10:11], off nt
	v_add_co_u32_e32 v54, vcc, 0xfef00000, v10
	s_nop 1
	v_addc_co_u32_e32 v55, vcc, -1, v11, vcc
	global_load_dwordx4 v[48:51], v[54:55], off nt
	v_lshl_add_u64 v[10:11], v[10:11], 0, s[12:13]
	v_lshl_add_u64 v[52:53], v[52:53], 0, s[10:11]
.LBB0_1352:
	v_add_u32_e32 v8, s8, v8
	v_cmp_le_i32_e32 vcc, s14, v8
	s_or_b64 s[6:7], vcc, s[6:7]
	s_waitcnt vmcnt(0) lgkmcnt(0)
	v_mov_b32_e32 v14, v40
	v_mov_b32_e32 v15, v41
	v_mov_b32_e32 v16, v42
	v_mov_b32_e32 v17, v43
	v_mov_b32_e32 v18, v44
	v_mov_b32_e32 v19, v45
	v_mov_b32_e32 v20, v46
	v_mov_b32_e32 v21, v47
	v_mov_b32_e32 v22, v48
	v_mov_b32_e32 v23, v49
	v_mov_b32_e32 v24, v50
	v_mov_b32_e32 v25, v51
	s_cbranch_vccnz .Lmlcomb_nopf
	global_load_dwordx4 v[40:43], v[52:53], off
	global_load_dwordx4 v[44:47], v[10:11], off nt
	v_add_co_u32_e32 v54, vcc, 0xfef00000, v10
	s_nop 1
	v_addc_co_u32_e32 v55, vcc, -1, v11, vcc
	global_load_dwordx4 v[48:51], v[54:55], off nt
	v_lshl_add_u64 v[10:11], v[10:11], 0, s[12:13]
	v_lshl_add_u64 v[52:53], v[52:53], 0, s[10:11]
.Lmlcomb_nopf:
	v_lshlrev_b32_e32 v9, 16, v14
	v_and_b32_e32 v28, 0xffff0000, v14
	v_lshlrev_b32_e32 v29, 16, v15
	v_and_b32_e32 v30, 0xffff0000, v15
	v_lshlrev_b32_e32 v31, 16, v16
	v_and_b32_e32 v32, 0xffff0000, v16
	v_lshlrev_b32_e32 v33, 16, v17
	v_and_b32_e32 v34, 0xffff0000, v17
	v_lshlrev_b32_e32 v14, 16, v21
	v_and_b32_e32 v15, 0xffff0000, v21
	v_lshlrev_b32_e32 v16, 16, v20
	v_and_b32_e32 v17, 0xffff0000, v20
	v_lshlrev_b32_e32 v20, 16, v19
	v_and_b32_e32 v21, 0xffff0000, v19
	v_lshlrev_b32_e32 v26, 16, v18
	v_and_b32_e32 v27, 0xffff0000, v18
	v_mul_f32_e32 v9, 0xbfb8aa3b, v9
	v_mul_f32_e32 v18, 0xbfb8aa3b, v28
	v_mul_f32_e32 v19, 0xbfb8aa3b, v29
	v_mul_f32_e32 v28, 0xbfb8aa3b, v30
	v_mul_f32_e32 v29, 0xbfb8aa3b, v31
	v_mul_f32_e32 v30, 0xbfb8aa3b, v32
	v_mul_f32_e32 v31, 0xbfb8aa3b, v33
	v_mul_f32_e32 v32, 0xbfb8aa3b, v34
	v_exp_f32_e32 v9, v9
	v_exp_f32_e32 v33, v18
	v_exp_f32_e32 v34, v19
	v_exp_f32_e32 v35, v28
	v_exp_f32_e32 v36, v29
	v_exp_f32_e32 v37, v30
	v_exp_f32_e32 v38, v31
	v_lshlrev_b32_e32 v18, 16, v25
	v_and_b32_e32 v19, 0xffff0000, v25
	v_lshlrev_b32_e32 v28, 16, v24
	v_and_b32_e32 v29, 0xffff0000, v24
	v_lshlrev_b32_e32 v24, 16, v23
	v_and_b32_e32 v25, 0xffff0000, v23
	v_lshlrev_b32_e32 v30, 16, v22
	v_and_b32_e32 v31, 0xffff0000, v22
	v_pk_add_f32 v[14:15], v[18:19], v[14:15]
	v_pk_add_f32 v[18:19], v[24:25], v[20:21]
	v_pk_add_f32 v[20:21], v[30:31], v[26:27]
	v_pk_add_f32 v[16:17], v[28:29], v[16:17]
	v_pk_mul_f32 v[28:29], v[20:21], v[20:21]
	v_pk_mul_f32 v[26:27], v[18:19], v[18:19]
	v_add_f32_e32 v28, v28, v29
	v_add_f32_e32 v9, 1.0, v9
	v_add_f32_e32 v26, v26, v28
	v_pk_mul_f32 v[24:25], v[16:17], v[16:17]
	v_rcp_f32_e32 v28, v9
	v_add_f32_e32 v9, v27, v26
	v_add_f32_e32 v9, v24, v9
	v_pk_mul_f32 v[22:23], v[14:15], v[14:15]
	v_add_f32_e32 v9, v25, v9
	v_add_f32_e32 v9, v22, v9
	v_add_f32_e32 v9, v23, v9
	v_exp_f32_e32 v32, v32
	v_add_f32_e32 v29, 1.0, v33
	v_add_f32_dpp v9, v9, v9 quad_perm:[1,0,3,2] row_mask:0xf bank_mask:0xf bound_ctrl:1
	v_add_f32_e32 v30, 1.0, v34
	v_add_f32_e32 v31, 1.0, v35
	v_add_f32_dpp v9, v9, v9 quad_perm:[2,3,0,1] row_mask:0xf bank_mask:0xf bound_ctrl:1
	v_add_f32_e32 v33, 1.0, v36
	v_add_f32_e32 v34, 1.0, v37
	v_add_f32_dpp v9, v9, v9 row_half_mirror row_mask:0xf bank_mask:0xf bound_ctrl:1
	v_add_f32_e32 v35, 1.0, v38
	v_add_f32_e32 v36, 1.0, v32
	v_add_f32_dpp v9, v9, v9 row_mirror row_mask:0xf bank_mask:0xf bound_ctrl:1
	v_fmamk_f32 v9, v9, 0x3c000000, v248
	v_mul_f32_e32 v22, 0x4b800000, v9
	v_cmp_gt_f32_e32 vcc, s9, v9
	v_rcp_f32_e32 v29, v29
	v_rcp_f32_e32 v30, v30
	v_cndmask_b32_e32 v9, v9, v22, vcc
	v_rsq_f32_e32 v9, v9
	v_rcp_f32_e32 v31, v31
	v_rcp_f32_e32 v32, v33
	v_rcp_f32_e32 v33, v34
	v_rcp_f32_e32 v34, v35
	v_rcp_f32_e32 v35, v36
	v_mul_f32_e32 v22, 0x45800000, v9
	v_cndmask_b32_e32 v22, v9, v22, vcc
	v_pk_mul_f32 v[20:21], v[20:21], v[22:23] op_sel_hi:[1,0]
	v_pk_mul_f32 v[18:19], v[18:19], v[22:23] op_sel_hi:[1,0]
	v_pk_mul_f32 v[16:17], v[16:17], v[22:23] op_sel_hi:[1,0]
	v_pk_mul_f32 v[14:15], v[14:15], v[22:23] op_sel_hi:[1,0]
	v_pk_mul_f32 v[20:21], v[4:5], v[20:21]
	v_pk_mul_f32 v[18:19], v[6:7], v[18:19]
	v_pk_mul_f32 v[16:17], v[0:1], v[16:17]
	v_pk_mul_f32 v[14:15], v[2:3], v[14:15]
	v_pk_mul_f32 v[20:21], v[28:29], v[20:21]
	v_pk_mul_f32 v[18:19], v[30:31], v[18:19]
	v_pk_mul_f32 v[16:17], v[32:33], v[16:17]
	v_pk_mul_f32 v[22:23], v[34:35], v[14:15]
	v_cvt_pk_bf16_f32 v14, v20, v21
	v_cvt_pk_bf16_f32 v15, v18, v19
	v_cvt_pk_bf16_f32 v16, v16, v17
	v_cvt_pk_bf16_f32 v17, v22, v23
	global_store_dwordx4 v[12:13], v[14:17], off
	v_lshl_add_u64 v[12:13], v[12:13], 0, s[10:11]
	s_andn2_b64 exec, exec, s[6:7]
	s_cbranch_execnz .LBB0_1352
